# prompt attention fast loop: hand-written softmax block (exp in place, plain f32 adds for the row sum instead of hipcc's v_pk_add_f32 pairs)
# speedup vs baseline: 1.0321x; 1.0130x over previous
.Lqf_454:
	s_nop 8
	v_exp_f32_e32 v80, v80
	v_exp_f32_e32 v96, v96
	v_exp_f32_e32 v81, v81
	v_exp_f32_e32 v97, v97
	v_add_f32_e32 v0, v80, v96
	v_exp_f32_e32 v82, v82
	v_exp_f32_e32 v98, v98
	v_add_f32_e32 v0, v0, v81
	v_add_f32_e32 v0, v0, v97
	v_cvt_pk_bf16_f32 v132, v80, v81
	v_cvt_pk_bf16_f32 v136, v96, v97
	v_exp_f32_e32 v83, v83
	v_exp_f32_e32 v99, v99
	v_add_f32_e32 v0, v0, v82
	v_add_f32_e32 v0, v0, v98
	v_exp_f32_e32 v84, v84
	v_exp_f32_e32 v100, v100
	v_add_f32_e32 v0, v0, v83
	v_add_f32_e32 v0, v0, v99
	v_cvt_pk_bf16_f32 v133, v82, v83
	v_cvt_pk_bf16_f32 v137, v98, v99
	v_exp_f32_e32 v85, v85
	v_exp_f32_e32 v101, v101
	v_add_f32_e32 v0, v0, v84
	v_add_f32_e32 v0, v0, v100
	v_exp_f32_e32 v86, v86
	v_exp_f32_e32 v102, v102
	v_add_f32_e32 v0, v0, v85
	v_add_f32_e32 v0, v0, v101
	v_cvt_pk_bf16_f32 v134, v84, v85
	v_cvt_pk_bf16_f32 v138, v100, v101
	v_exp_f32_e32 v87, v87
	v_exp_f32_e32 v103, v103
	v_add_f32_e32 v0, v0, v86
	v_add_f32_e32 v0, v0, v102
	v_exp_f32_e32 v88, v88
	v_exp_f32_e32 v104, v104
	v_add_f32_e32 v0, v0, v87
	v_add_f32_e32 v0, v0, v103
	v_cvt_pk_bf16_f32 v135, v86, v87
	v_cvt_pk_bf16_f32 v139, v102, v103
	v_exp_f32_e32 v89, v89
	v_exp_f32_e32 v105, v105
	v_add_f32_e32 v0, v0, v88
	v_add_f32_e32 v0, v0, v104
	v_exp_f32_e32 v90, v90
	v_exp_f32_e32 v106, v106
	v_add_f32_e32 v0, v0, v89
	v_add_f32_e32 v0, v0, v105
	v_cvt_pk_bf16_f32 v140, v88, v89
	v_cvt_pk_bf16_f32 v144, v104, v105
	v_exp_f32_e32 v91, v91
	v_exp_f32_e32 v107, v107
	v_add_f32_e32 v0, v0, v90
	v_add_f32_e32 v0, v0, v106
	v_exp_f32_e32 v92, v92
	v_exp_f32_e32 v108, v108
	v_add_f32_e32 v0, v0, v91
	v_add_f32_e32 v0, v0, v107
	v_cvt_pk_bf16_f32 v141, v90, v91
	v_cvt_pk_bf16_f32 v145, v106, v107
	v_exp_f32_e32 v93, v93
	v_exp_f32_e32 v109, v109
	v_add_f32_e32 v0, v0, v92
	v_add_f32_e32 v0, v0, v108
	v_exp_f32_e32 v94, v94
	v_exp_f32_e32 v110, v110
	v_add_f32_e32 v0, v0, v93
	v_add_f32_e32 v0, v0, v109
	v_cvt_pk_bf16_f32 v142, v92, v93
	v_cvt_pk_bf16_f32 v146, v108, v109
	v_exp_f32_e32 v95, v95
	v_exp_f32_e32 v111, v111
	v_add_f32_e32 v0, v0, v94
	v_add_f32_e32 v0, v0, v110
	s_nop 0
	v_add_f32_e32 v0, v0, v95
	v_add_f32_e32 v0, v0, v111
	v_cvt_pk_bf16_f32 v143, v94, v95
	v_cvt_pk_bf16_f32 v147, v110, v111
	v_add_f32_e32 v175, v175, v0

.Lqf_461:
	s_nop 8
	v_exp_f32_e32 v80, v80
	v_exp_f32_e32 v96, v96
	v_exp_f32_e32 v81, v81
	v_exp_f32_e32 v97, v97
	v_add_f32_e32 v0, v80, v96
	v_exp_f32_e32 v82, v82
	v_exp_f32_e32 v98, v98
	v_add_f32_e32 v0, v0, v81
	v_add_f32_e32 v0, v0, v97
	v_cvt_pk_bf16_f32 v148, v80, v81
	v_cvt_pk_bf16_f32 v152, v96, v97
	v_exp_f32_e32 v83, v83
	v_exp_f32_e32 v99, v99
	v_add_f32_e32 v0, v0, v82
	v_add_f32_e32 v0, v0, v98
	v_exp_f32_e32 v84, v84
	v_exp_f32_e32 v100, v100
	v_add_f32_e32 v0, v0, v83
	v_add_f32_e32 v0, v0, v99
	v_cvt_pk_bf16_f32 v149, v82, v83
	v_cvt_pk_bf16_f32 v153, v98, v99
	v_exp_f32_e32 v85, v85
	v_exp_f32_e32 v101, v101
	v_add_f32_e32 v0, v0, v84
	v_add_f32_e32 v0, v0, v100
	v_exp_f32_e32 v86, v86
	v_exp_f32_e32 v102, v102
	v_add_f32_e32 v0, v0, v85
	v_add_f32_e32 v0, v0, v101
	v_cvt_pk_bf16_f32 v150, v84, v85
	v_cvt_pk_bf16_f32 v154, v100, v101
	v_exp_f32_e32 v87, v87
	v_exp_f32_e32 v103, v103
	v_add_f32_e32 v0, v0, v86
	v_add_f32_e32 v0, v0, v102
	v_exp_f32_e32 v88, v88
	v_exp_f32_e32 v104, v104
	v_add_f32_e32 v0, v0, v87
	v_add_f32_e32 v0, v0, v103
	v_cvt_pk_bf16_f32 v151, v86, v87
	v_cvt_pk_bf16_f32 v155, v102, v103
	v_exp_f32_e32 v89, v89
	v_exp_f32_e32 v105, v105
	v_add_f32_e32 v0, v0, v88
	v_add_f32_e32 v0, v0, v104
	v_exp_f32_e32 v90, v90
	v_exp_f32_e32 v106, v106
	v_add_f32_e32 v0, v0, v89
	v_add_f32_e32 v0, v0, v105
	v_cvt_pk_bf16_f32 v156, v88, v89
	v_cvt_pk_bf16_f32 v160, v104, v105
	v_exp_f32_e32 v91, v91
	v_exp_f32_e32 v107, v107
	v_add_f32_e32 v0, v0, v90
	v_add_f32_e32 v0, v0, v106
	v_exp_f32_e32 v92, v92
	v_exp_f32_e32 v108, v108
	v_add_f32_e32 v0, v0, v91
	v_add_f32_e32 v0, v0, v107
	v_cvt_pk_bf16_f32 v157, v90, v91
	v_cvt_pk_bf16_f32 v161, v106, v107
	v_exp_f32_e32 v93, v93
	v_exp_f32_e32 v109, v109
	v_add_f32_e32 v0, v0, v92
	v_add_f32_e32 v0, v0, v108
	v_exp_f32_e32 v94, v94
	v_exp_f32_e32 v110, v110
	v_add_f32_e32 v0, v0, v93
	v_add_f32_e32 v0, v0, v109
	v_cvt_pk_bf16_f32 v158, v92, v93
	v_cvt_pk_bf16_f32 v162, v108, v109
	v_exp_f32_e32 v95, v95
	v_exp_f32_e32 v111, v111
	v_add_f32_e32 v0, v0, v94
	v_add_f32_e32 v0, v0, v110
	s_nop 0
	v_add_f32_e32 v0, v0, v95
	v_add_f32_e32 v0, v0, v111
	v_cvt_pk_bf16_f32 v159, v94, v95
	v_cvt_pk_bf16_f32 v163, v110, v111
	v_add_f32_e32 v175, v175, v0
